# weight-conversion tr_item: 16 per-row gain loads issued together instead of one serialized round trip each
# speedup vs baseline: 1.0102x; 1.0016x over previous
.LBB0_828:
	s_andn2_b64 vcc, exec, s[10:11]
	s_cbranch_vccnz .LBB0_825
	s_mul_hi_i32 s0, s7, 0x2e8ba2e9
	s_lshr_b32 s10, s0, 31
	s_ashr_i32 s0, s0, 4
	s_add_i32 s10, s0, s10
	s_mul_i32 s0, s10, 0xffffffa8
	s_add_i32 s11, s7, s0
	s_mul_i32 s0, s11, 47
	s_sext_i32_i16 s12, s0
	s_ashr_i32 s12, s12, 11
	s_bfe_u32 s0, s0, 0x1000f
	s_add_i32 s0, s12, s0
	s_mul_i32 s12, s0, 44
	s_sub_i32 s12, s11, s12
	s_sext_i32_i8 s17, s12
	s_lshl_b32 s12, s17, 6
	s_add_i32 s11, s11, 43
	s_cmpk_lt_u32 s11, 0x57
	s_cselect_b32 s11, s75, s77
	s_cselect_b32 s18, s74, s76
	s_ashr_i32 s13, s12, 31
	s_lshl_b32 s10, s10, 6
	s_lshl_b64 s[14:15], s[12:13], 2
	s_add_u32 s14, s18, s14
	v_or_b32_e32 v74, s10, v66
	s_addc_u32 s15, s11, s15
	v_lshl_add_u64 v[2:3], s[14:15], 0, v[0:1]
	v_or_b32_e32 v6, 4, v74
	v_mad_i64_i32 v[4:5], s[14:15], v74, s67, v[2:3]
	v_mad_i64_i32 v[6:7], s[14:15], v6, s67, v[2:3]
	global_load_dwordx4 v[62:65], v[4:5], off
	global_load_dwordx4 v[58:61], v[6:7], off
	v_or_b32_e32 v4, 8, v74
	v_or_b32_e32 v6, 12, v74
	v_mad_i64_i32 v[4:5], s[14:15], v4, s67, v[2:3]
	v_mad_i64_i32 v[6:7], s[14:15], v6, s67, v[2:3]
	global_load_dwordx4 v[54:57], v[4:5], off
	global_load_dwordx4 v[50:53], v[6:7], off
	v_or_b32_e32 v4, 16, v74
	v_or_b32_e32 v6, 20, v74
	v_mad_i64_i32 v[4:5], s[14:15], v4, s67, v[2:3]
	v_mad_i64_i32 v[6:7], s[14:15], v6, s67, v[2:3]
	global_load_dwordx4 v[46:49], v[4:5], off
	global_load_dwordx4 v[42:45], v[6:7], off
	v_or_b32_e32 v4, 24, v74
	v_or_b32_e32 v6, 28, v74
	v_mad_i64_i32 v[4:5], s[14:15], v4, s67, v[2:3]
	v_mad_i64_i32 v[6:7], s[14:15], v6, s67, v[2:3]
	global_load_dwordx4 v[38:41], v[4:5], off
	global_load_dwordx4 v[34:37], v[6:7], off
	v_or_b32_e32 v4, 32, v74
	v_or_b32_e32 v6, 36, v74
	v_mad_i64_i32 v[4:5], s[14:15], v4, s67, v[2:3]
	v_mad_i64_i32 v[6:7], s[14:15], v6, s67, v[2:3]
	global_load_dwordx4 v[30:33], v[4:5], off
	global_load_dwordx4 v[26:29], v[6:7], off
	v_or_b32_e32 v4, 40, v74
	v_or_b32_e32 v6, 44, v74
	v_mad_i64_i32 v[4:5], s[14:15], v4, s67, v[2:3]
	v_mad_i64_i32 v[6:7], s[14:15], v6, s67, v[2:3]
	global_load_dwordx4 v[22:25], v[4:5], off
	global_load_dwordx4 v[18:21], v[6:7], off
	v_or_b32_e32 v4, 48, v74
	v_or_b32_e32 v6, 52, v74
	v_mad_i64_i32 v[4:5], s[14:15], v4, s67, v[2:3]
	v_mad_i64_i32 v[6:7], s[14:15], v6, s67, v[2:3]
	global_load_dwordx4 v[14:17], v[4:5], off
	global_load_dwordx4 v[10:13], v[6:7], off
	v_or_b32_e32 v4, 56, v74
	v_or_b32_e32 v6, 60, v74
	v_mad_i64_i32 v[4:5], s[14:15], v4, s67, v[2:3]
	v_mad_i64_i32 v[2:3], s[14:15], v6, s67, v[2:3]
	global_load_dwordx4 v[6:9], v[4:5], off
	s_nop 0
	global_load_dwordx4 v[2:5], v[2:3], off
	v_cndmask_b32_e64 v75, 0, 1, s[24:25]
	v_cmp_ne_u32_e64 s[34:35], 1, v75
	s_andn2_b64 vcc, exec, s[24:25]
	s_cbranch_vccnz .LBB0_852
	v_ashrrev_i32_e32 v75, 31, v74
	v_lshl_add_u64 v[74:75], v[74:75], 2, s[72:73]
	global_load_dword v122, v[74:75], off
	global_load_dword v123, v[74:75], off offset:16
	global_load_dword v124, v[74:75], off offset:32
	global_load_dword v125, v[74:75], off offset:48
	global_load_dword v126, v[74:75], off offset:64
	global_load_dword v127, v[74:75], off offset:80
	global_load_dword v128, v[74:75], off offset:96
	global_load_dword v129, v[74:75], off offset:112
	global_load_dword v130, v[74:75], off offset:128
	global_load_dword v131, v[74:75], off offset:144
	global_load_dword v132, v[74:75], off offset:160
	global_load_dword v133, v[74:75], off offset:176
	global_load_dword v134, v[74:75], off offset:192
	global_load_dword v135, v[74:75], off offset:208
	global_load_dword v136, v[74:75], off offset:224
	global_load_dword v137, v[74:75], off offset:240
	s_ashr_i32 s11, s10, 31
	s_waitcnt vmcnt(0)
	v_mov_b32_e32 v74, v122
	v_pk_mul_f32 v[92:93], v[62:63], v[74:75] op_sel_hi:[1,0]
	v_pk_mul_f32 v[74:75], v[64:65], v[74:75] op_sel_hi:[1,0]
	ds_write2_b32 v87, v74, v75 offset0:2 offset1:3
	v_lshl_add_u64 v[74:75], s[10:11], 0, v[66:67]
	v_lshl_add_u64 v[74:75], v[74:75], 2, s[72:73]
	v_mov_b32_e32 v74, v123
	ds_write2_b32 v87, v92, v93 offset1:1
	s_cbranch_execnz .LBB0_832

.LBB0_832:
	s_waitcnt vmcnt(0)
	v_pk_mul_f32 v[58:59], v[58:59], v[74:75] op_sel_hi:[1,0]
	ds_write2_b32 v85, v58, v59 offset1:1
	v_pk_mul_f32 v[58:59], v[60:61], v[74:75] op_sel_hi:[1,0]
	s_and_b64 vcc, exec, s[34:35]
	ds_write2_b32 v85, v58, v59 offset0:2 offset1:3
	s_cbranch_vccnz .LBB0_853
	s_ashr_i32 s11, s10, 31
	v_lshl_add_u64 v[58:59], s[10:11], 0, v[66:67]
	v_lshl_add_u64 v[58:59], v[58:59], 2, s[72:73]
	v_mov_b32_e32 v60, v124
	s_nop 0
	v_mov_b32_e32 v58, v125
	s_waitcnt vmcnt(1)
	v_pk_mul_f32 v[62:63], v[54:55], v[60:61] op_sel_hi:[1,0]
	v_pk_mul_f32 v[60:61], v[56:57], v[60:61] op_sel_hi:[1,0]
	ds_write2_b32 v88, v62, v63 offset1:1
	ds_write2_b32 v88, v60, v61 offset0:2 offset1:3
	s_cbranch_execnz .LBB0_835

.LBB0_835:
	s_waitcnt vmcnt(0)
	v_pk_mul_f32 v[50:51], v[50:51], v[58:59] op_sel_hi:[1,0]
	ds_write2_b32 v86, v50, v51 offset1:1
	v_pk_mul_f32 v[50:51], v[52:53], v[58:59] op_sel_hi:[1,0]
	s_and_b64 vcc, exec, s[34:35]
	ds_write2_b32 v86, v50, v51 offset0:2 offset1:3
	s_cbranch_vccnz .LBB0_854
	s_ashr_i32 s11, s10, 31
	v_lshl_add_u64 v[50:51], s[10:11], 0, v[66:67]
	v_lshl_add_u64 v[50:51], v[50:51], 2, s[72:73]
	v_mov_b32_e32 v52, v126
	s_nop 0
	v_mov_b32_e32 v50, v127
	s_waitcnt vmcnt(1)
	v_pk_mul_f32 v[54:55], v[46:47], v[52:53] op_sel_hi:[1,0]
	v_pk_mul_f32 v[52:53], v[48:49], v[52:53] op_sel_hi:[1,0]
	ds_write2_b32 v89, v54, v55 offset1:1
	ds_write2_b32 v89, v52, v53 offset0:2 offset1:3
	s_cbranch_execnz .LBB0_838

.LBB0_838:
	s_waitcnt vmcnt(0)
	v_pk_mul_f32 v[42:43], v[42:43], v[50:51] op_sel_hi:[1,0]
	v_add_u32_e32 v46, 0x410, v89
	ds_write2_b32 v46, v42, v43 offset1:1
	v_pk_mul_f32 v[42:43], v[44:45], v[50:51] op_sel_hi:[1,0]
	v_add_u32_e32 v44, 0x418, v89
	ds_write2_b32 v44, v42, v43 offset1:1
	s_and_b64 vcc, exec, s[34:35]
	v_add_u32_e32 v43, 0x820, v89
	v_add_u32_e32 v44, 0x828, v89
	s_cbranch_vccnz .LBB0_855
	s_ashr_i32 s11, s10, 31
	v_lshl_add_u64 v[46:47], s[10:11], 0, v[66:67]
	v_lshl_add_u64 v[46:47], v[46:47], 2, s[72:73]
	v_mov_b32_e32 v42, v128
	s_waitcnt vmcnt(0)
	v_pk_mul_f32 v[48:49], v[38:39], v[42:43] op_sel_hi:[1,0]
	ds_write2_b32 v43, v48, v49 offset1:1
	v_pk_mul_f32 v[48:49], v[40:41], v[42:43] op_sel_hi:[1,0]
	v_mov_b32_e32 v42, v129
	ds_write2_b32 v44, v48, v49 offset1:1
	s_cbranch_execnz .LBB0_841

.LBB0_841:
	s_waitcnt vmcnt(0)
	v_pk_mul_f32 v[34:35], v[34:35], v[42:43] op_sel_hi:[1,0]
	v_add_u32_e32 v38, 0xc30, v89
	ds_write2_b32 v38, v34, v35 offset1:1
	v_pk_mul_f32 v[34:35], v[36:37], v[42:43] op_sel_hi:[1,0]
	v_add_u32_e32 v36, 0xc38, v89
	ds_write2_b32 v36, v34, v35 offset1:1
	s_and_b64 vcc, exec, s[34:35]
	v_add_u32_e32 v35, 0x1040, v89
	v_add_u32_e32 v36, 0x1048, v89
	s_cbranch_vccnz .LBB0_856
	s_ashr_i32 s11, s10, 31
	v_lshl_add_u64 v[38:39], s[10:11], 0, v[66:67]
	v_lshl_add_u64 v[38:39], v[38:39], 2, s[72:73]
	v_mov_b32_e32 v34, v130
	s_waitcnt vmcnt(0)
	v_pk_mul_f32 v[40:41], v[30:31], v[34:35] op_sel_hi:[1,0]
	ds_write2_b32 v35, v40, v41 offset1:1
	v_pk_mul_f32 v[40:41], v[32:33], v[34:35] op_sel_hi:[1,0]
	v_mov_b32_e32 v34, v131
	ds_write2_b32 v36, v40, v41 offset1:1
	s_cbranch_execnz .LBB0_844

.LBB0_844:
	s_waitcnt vmcnt(0)
	v_pk_mul_f32 v[26:27], v[26:27], v[34:35] op_sel_hi:[1,0]
	v_add_u32_e32 v30, 0x1450, v89
	ds_write2_b32 v30, v26, v27 offset1:1
	v_pk_mul_f32 v[26:27], v[28:29], v[34:35] op_sel_hi:[1,0]
	v_add_u32_e32 v28, 0x1458, v89
	ds_write2_b32 v28, v26, v27 offset1:1
	s_and_b64 vcc, exec, s[34:35]
	v_add_u32_e32 v27, 0x1860, v89
	v_add_u32_e32 v28, 0x1868, v89
	s_cbranch_vccnz .LBB0_857
	s_ashr_i32 s11, s10, 31
	v_lshl_add_u64 v[30:31], s[10:11], 0, v[66:67]
	v_lshl_add_u64 v[30:31], v[30:31], 2, s[72:73]
	v_mov_b32_e32 v26, v132
	s_waitcnt vmcnt(0)
	v_pk_mul_f32 v[32:33], v[22:23], v[26:27] op_sel_hi:[1,0]
	ds_write2_b32 v27, v32, v33 offset1:1
	v_pk_mul_f32 v[32:33], v[24:25], v[26:27] op_sel_hi:[1,0]
	v_mov_b32_e32 v26, v133
	ds_write2_b32 v28, v32, v33 offset1:1
	s_cbranch_execnz .LBB0_847

.LBB0_847:
	s_waitcnt vmcnt(0)
	v_pk_mul_f32 v[18:19], v[18:19], v[26:27] op_sel_hi:[1,0]
	v_add_u32_e32 v22, 0x1c70, v89
	ds_write2_b32 v22, v18, v19 offset1:1
	v_pk_mul_f32 v[18:19], v[20:21], v[26:27] op_sel_hi:[1,0]
	v_add_u32_e32 v20, 0x1c78, v89
	ds_write2_b32 v20, v18, v19 offset1:1
	s_and_b64 vcc, exec, s[34:35]
	v_add_u32_e32 v19, 0x2080, v89
	v_add_u32_e32 v20, 0x2088, v89
	s_cbranch_vccnz .LBB0_858
	s_ashr_i32 s11, s10, 31
	v_lshl_add_u64 v[22:23], s[10:11], 0, v[66:67]
	v_lshl_add_u64 v[22:23], v[22:23], 2, s[72:73]
	v_mov_b32_e32 v18, v134
	s_waitcnt vmcnt(0)
	v_pk_mul_f32 v[24:25], v[14:15], v[18:19] op_sel_hi:[1,0]
	ds_write2_b32 v19, v24, v25 offset1:1
	v_pk_mul_f32 v[24:25], v[16:17], v[18:19] op_sel_hi:[1,0]
	v_mov_b32_e32 v18, v135
	ds_write2_b32 v20, v24, v25 offset1:1
	s_cbranch_execnz .LBB0_850

.LBB0_850:
	s_waitcnt vmcnt(0)
	v_pk_mul_f32 v[10:11], v[10:11], v[18:19] op_sel_hi:[1,0]
	v_add_u32_e32 v14, 0x2490, v89
	ds_write2_b32 v14, v10, v11 offset1:1
	v_pk_mul_f32 v[10:11], v[12:13], v[18:19] op_sel_hi:[1,0]
	v_add_u32_e32 v12, 0x2498, v89
	ds_write2_b32 v12, v10, v11 offset1:1
	s_and_b64 vcc, exec, s[34:35]
	v_add_u32_e32 v11, 0x28a0, v89
	v_add_u32_e32 v12, 0x28a8, v89
	s_cbranch_vccnz .LBB0_859
	s_ashr_i32 s11, s10, 31
	v_lshl_add_u64 v[14:15], s[10:11], 0, v[66:67]
	v_lshl_add_u64 v[14:15], v[14:15], 2, s[72:73]
	v_mov_b32_e32 v10, v136
	s_waitcnt vmcnt(0)
	v_pk_mul_f32 v[16:17], v[6:7], v[10:11] op_sel_hi:[1,0]
	ds_write2_b32 v11, v16, v17 offset1:1
	v_pk_mul_f32 v[16:17], v[8:9], v[10:11] op_sel_hi:[1,0]
	v_mov_b32_e32 v10, v137
	ds_write2_b32 v12, v16, v17 offset1:1
	s_cbranch_execnz .LBB0_824
	s_branch .LBB0_823

.LBB0_908:
	s_or_b64 exec, exec, s[14:15]
	v_readlane_b32 s14, v253, 22
	v_readlane_b32 s15, v253, 23
	s_andn2_b64 vcc, exec, s[14:15]
	s_nop 0
	v_cndmask_b32_e64 v0, 0, 1, s[14:15]
	v_cmp_ne_u32_e64 s[34:35], 1, v0
	s_cbranch_vccnz .LBB0_931
	v_ashrrev_i32_e32 v83, 31, v82
	v_lshl_add_u64 v[82:83], v[82:83], 2, s[80:81]
	global_load_dword v122, v[82:83], off
	global_load_dword v123, v[82:83], off offset:16
	global_load_dword v124, v[82:83], off offset:32
	global_load_dword v125, v[82:83], off offset:48
	global_load_dword v126, v[82:83], off offset:64
	global_load_dword v127, v[82:83], off offset:80
	global_load_dword v128, v[82:83], off offset:96
	global_load_dword v129, v[82:83], off offset:112
	global_load_dword v130, v[82:83], off offset:128
	global_load_dword v131, v[82:83], off offset:144
	global_load_dword v132, v[82:83], off offset:160
	global_load_dword v133, v[82:83], off offset:176
	global_load_dword v134, v[82:83], off offset:192
	global_load_dword v135, v[82:83], off offset:208
	global_load_dword v136, v[82:83], off offset:224
	global_load_dword v137, v[82:83], off offset:240
	s_ashr_i32 s13, s12, 31
	s_waitcnt vmcnt(0)
	v_mov_b32_e32 v0, v122
	v_pk_mul_f32 v[82:83], v[62:63], v[0:1] op_sel_hi:[1,0]
	ds_write2_b32 v69, v82, v83 offset1:1
	v_pk_mul_f32 v[82:83], v[64:65], v[0:1] op_sel_hi:[1,0]
	ds_write2_b32 v69, v82, v83 offset0:2 offset1:3
	v_lshl_add_u64 v[82:83], s[12:13], 0, v[66:67]
	v_lshl_add_u64 v[82:83], v[82:83], 2, s[80:81]
	v_mov_b32_e32 v0, v123
	s_cbranch_execnz .LBB0_911

.LBB0_911:
	s_waitcnt vmcnt(0)
	v_pk_mul_f32 v[58:59], v[58:59], v[0:1] op_sel_hi:[1,0]
	ds_write2_b32 v95, v58, v59 offset1:1
	v_pk_mul_f32 v[58:59], v[60:61], v[0:1] op_sel_hi:[1,0]
	s_and_b64 vcc, exec, s[34:35]
	ds_write2_b32 v95, v58, v59 offset0:2 offset1:3
	s_cbranch_vccnz .LBB0_932
	s_ashr_i32 s13, s12, 31
	v_lshl_add_u64 v[58:59], s[12:13], 0, v[66:67]
	v_lshl_add_u64 v[58:59], v[58:59], 2, s[80:81]
	v_mov_b32_e32 v0, v124
	s_waitcnt vmcnt(0)
	v_pk_mul_f32 v[60:61], v[54:55], v[0:1] op_sel_hi:[1,0]
	ds_write2_b32 v97, v60, v61 offset1:1
	v_pk_mul_f32 v[60:61], v[56:57], v[0:1] op_sel_hi:[1,0]
	v_mov_b32_e32 v0, v125
	ds_write2_b32 v97, v60, v61 offset0:2 offset1:3
	s_cbranch_execnz .LBB0_914

.LBB0_914:
	s_waitcnt vmcnt(0)
	v_pk_mul_f32 v[50:51], v[50:51], v[0:1] op_sel_hi:[1,0]
	ds_write2_b32 v96, v50, v51 offset1:1
	v_pk_mul_f32 v[50:51], v[52:53], v[0:1] op_sel_hi:[1,0]
	s_and_b64 vcc, exec, s[34:35]
	ds_write2_b32 v96, v50, v51 offset0:2 offset1:3
	s_cbranch_vccnz .LBB0_933
	s_ashr_i32 s13, s12, 31
	v_lshl_add_u64 v[50:51], s[12:13], 0, v[66:67]
	v_lshl_add_u64 v[50:51], v[50:51], 2, s[80:81]
	v_mov_b32_e32 v0, v126
	s_waitcnt vmcnt(0)
	v_pk_mul_f32 v[52:53], v[46:47], v[0:1] op_sel_hi:[1,0]
	ds_write2_b32 v98, v52, v53 offset1:1
	v_pk_mul_f32 v[52:53], v[48:49], v[0:1] op_sel_hi:[1,0]
	v_mov_b32_e32 v0, v127
	ds_write2_b32 v98, v52, v53 offset0:2 offset1:3
	s_cbranch_execnz .LBB0_917

.LBB0_917:
	s_waitcnt vmcnt(0)
	v_pk_mul_f32 v[42:43], v[42:43], v[0:1] op_sel_hi:[1,0]
	v_add_u32_e32 v46, 0x410, v98
	ds_write2_b32 v46, v42, v43 offset1:1
	v_pk_mul_f32 v[42:43], v[44:45], v[0:1] op_sel_hi:[1,0]
	v_add_u32_e32 v0, 0x418, v98
	ds_write2_b32 v0, v42, v43 offset1:1
	s_and_b64 vcc, exec, s[34:35]
	v_add_u32_e32 v42, 0x820, v98
	v_add_u32_e32 v43, 0x828, v98
	s_cbranch_vccnz .LBB0_934
	s_ashr_i32 s13, s12, 31
	v_lshl_add_u64 v[44:45], s[12:13], 0, v[66:67]
	v_lshl_add_u64 v[44:45], v[44:45], 2, s[80:81]
	v_mov_b32_e32 v0, v128
	s_waitcnt vmcnt(0)
	v_pk_mul_f32 v[46:47], v[38:39], v[0:1] op_sel_hi:[1,0]
	ds_write2_b32 v42, v46, v47 offset1:1
	v_pk_mul_f32 v[46:47], v[40:41], v[0:1] op_sel_hi:[1,0]
	v_mov_b32_e32 v0, v129
	ds_write2_b32 v43, v46, v47 offset1:1
	s_cbranch_execnz .LBB0_920

.LBB0_920:
	s_waitcnt vmcnt(0)
	v_pk_mul_f32 v[34:35], v[34:35], v[0:1] op_sel_hi:[1,0]
	v_add_u32_e32 v38, 0xc30, v98
	ds_write2_b32 v38, v34, v35 offset1:1
	v_pk_mul_f32 v[34:35], v[36:37], v[0:1] op_sel_hi:[1,0]
	v_add_u32_e32 v0, 0xc38, v98
	ds_write2_b32 v0, v34, v35 offset1:1
	s_and_b64 vcc, exec, s[34:35]
	v_add_u32_e32 v34, 0x1040, v98
	v_add_u32_e32 v35, 0x1048, v98
	s_cbranch_vccnz .LBB0_935
	s_ashr_i32 s13, s12, 31
	v_lshl_add_u64 v[36:37], s[12:13], 0, v[66:67]
	v_lshl_add_u64 v[36:37], v[36:37], 2, s[80:81]
	v_mov_b32_e32 v0, v130
	s_waitcnt vmcnt(0)
	v_pk_mul_f32 v[38:39], v[30:31], v[0:1] op_sel_hi:[1,0]
	ds_write2_b32 v34, v38, v39 offset1:1
	v_pk_mul_f32 v[38:39], v[32:33], v[0:1] op_sel_hi:[1,0]
	v_mov_b32_e32 v0, v131
	ds_write2_b32 v35, v38, v39 offset1:1
	s_cbranch_execnz .LBB0_923

.LBB0_923:
	s_waitcnt vmcnt(0)
	v_pk_mul_f32 v[26:27], v[26:27], v[0:1] op_sel_hi:[1,0]
	v_add_u32_e32 v30, 0x1450, v98
	ds_write2_b32 v30, v26, v27 offset1:1
	v_pk_mul_f32 v[26:27], v[28:29], v[0:1] op_sel_hi:[1,0]
	v_add_u32_e32 v0, 0x1458, v98
	ds_write2_b32 v0, v26, v27 offset1:1
	s_and_b64 vcc, exec, s[34:35]
	v_add_u32_e32 v26, 0x1860, v98
	v_add_u32_e32 v27, 0x1868, v98
	s_cbranch_vccnz .LBB0_936
	s_ashr_i32 s13, s12, 31
	v_lshl_add_u64 v[28:29], s[12:13], 0, v[66:67]
	v_lshl_add_u64 v[28:29], v[28:29], 2, s[80:81]
	v_mov_b32_e32 v0, v132
	s_waitcnt vmcnt(0)
	v_pk_mul_f32 v[30:31], v[22:23], v[0:1] op_sel_hi:[1,0]
	ds_write2_b32 v26, v30, v31 offset1:1
	v_pk_mul_f32 v[30:31], v[24:25], v[0:1] op_sel_hi:[1,0]
	v_mov_b32_e32 v0, v133
	ds_write2_b32 v27, v30, v31 offset1:1
	s_cbranch_execnz .LBB0_926

.LBB0_926:
	s_waitcnt vmcnt(0)
	v_pk_mul_f32 v[18:19], v[18:19], v[0:1] op_sel_hi:[1,0]
	v_add_u32_e32 v22, 0x1c70, v98
	ds_write2_b32 v22, v18, v19 offset1:1
	v_pk_mul_f32 v[18:19], v[20:21], v[0:1] op_sel_hi:[1,0]
	v_add_u32_e32 v0, 0x1c78, v98
	ds_write2_b32 v0, v18, v19 offset1:1
	s_and_b64 vcc, exec, s[34:35]
	v_add_u32_e32 v18, 0x2080, v98
	v_add_u32_e32 v19, 0x2088, v98
	s_cbranch_vccnz .LBB0_937
	s_ashr_i32 s13, s12, 31
	v_lshl_add_u64 v[20:21], s[12:13], 0, v[66:67]
	v_lshl_add_u64 v[20:21], v[20:21], 2, s[80:81]
	v_mov_b32_e32 v0, v134
	s_waitcnt vmcnt(0)
	v_pk_mul_f32 v[22:23], v[14:15], v[0:1] op_sel_hi:[1,0]
	ds_write2_b32 v18, v22, v23 offset1:1
	v_pk_mul_f32 v[22:23], v[16:17], v[0:1] op_sel_hi:[1,0]
	v_mov_b32_e32 v0, v135
	ds_write2_b32 v19, v22, v23 offset1:1
	s_cbranch_execnz .LBB0_929

.LBB0_929:
	s_waitcnt vmcnt(0)
	v_pk_mul_f32 v[10:11], v[10:11], v[0:1] op_sel_hi:[1,0]
	v_add_u32_e32 v14, 0x2490, v98
	ds_write2_b32 v14, v10, v11 offset1:1
	v_pk_mul_f32 v[10:11], v[12:13], v[0:1] op_sel_hi:[1,0]
	v_add_u32_e32 v0, 0x2498, v98
	ds_write2_b32 v0, v10, v11 offset1:1
	s_and_b64 vcc, exec, s[34:35]
	v_add_u32_e32 v10, 0x28a0, v98
	v_add_u32_e32 v11, 0x28a8, v98
	s_cbranch_vccnz .LBB0_938
	s_ashr_i32 s13, s12, 31
	v_lshl_add_u64 v[12:13], s[12:13], 0, v[66:67]
	v_lshl_add_u64 v[12:13], v[12:13], 2, s[80:81]
	v_mov_b32_e32 v0, v136
	s_waitcnt vmcnt(0)
	v_pk_mul_f32 v[14:15], v[6:7], v[0:1] op_sel_hi:[1,0]
	ds_write2_b32 v10, v14, v15 offset1:1
	v_pk_mul_f32 v[14:15], v[8:9], v[0:1] op_sel_hi:[1,0]
	v_mov_b32_e32 v0, v137
	ds_write2_b32 v11, v14, v15 offset1:1
	s_cbranch_execnz .LBB0_863
	s_branch .LBB0_862

.LBB0_952:
	s_andn2_b64 vcc, exec, s[10:11]
	s_cbranch_vccnz .LBB0_949
	s_mul_hi_i32 s0, s8, 0x2e8ba2e9
	s_lshr_b32 s10, s0, 31
	s_ashr_i32 s0, s0, 4
	s_add_i32 s10, s0, s10
	s_mul_i32 s0, s10, 0xffffffa8
	s_add_i32 s11, s8, s0
	s_mul_i32 s0, s11, 47
	s_sext_i32_i16 s12, s0
	s_ashr_i32 s12, s12, 11
	s_bfe_u32 s0, s0, 0x1000f
	s_add_i32 s0, s12, s0
	s_mul_i32 s12, s0, 44
	s_sub_i32 s12, s11, s12
	s_sext_i32_i8 s16, s12
	s_lshl_b32 s12, s16, 6
	s_add_i32 s11, s11, 43
	s_cmpk_lt_u32 s11, 0x57
	s_cselect_b32 s13, s74, s76
	s_cselect_b32 s11, s75, s77
	s_add_u32 s17, s13, s7
	s_addc_u32 s11, s11, 0
	s_ashr_i32 s13, s12, 31
	s_lshl_b32 s10, s10, 6
	s_lshl_b64 s[14:15], s[12:13], 2
	s_add_u32 s14, s17, s14
	v_or_b32_e32 v74, s10, v66
	s_addc_u32 s15, s11, s15
	v_lshl_add_u64 v[2:3], s[14:15], 0, v[0:1]
	v_or_b32_e32 v6, 4, v74
	v_mad_i64_i32 v[4:5], s[14:15], v74, s67, v[2:3]
	v_mad_i64_i32 v[6:7], s[14:15], v6, s67, v[2:3]
	global_load_dwordx4 v[62:65], v[4:5], off
	global_load_dwordx4 v[58:61], v[6:7], off
	v_or_b32_e32 v4, 8, v74
	v_or_b32_e32 v6, 12, v74
	v_mad_i64_i32 v[4:5], s[14:15], v4, s67, v[2:3]
	v_mad_i64_i32 v[6:7], s[14:15], v6, s67, v[2:3]
	global_load_dwordx4 v[54:57], v[4:5], off
	global_load_dwordx4 v[50:53], v[6:7], off
	v_or_b32_e32 v4, 16, v74
	v_or_b32_e32 v6, 20, v74
	v_mad_i64_i32 v[4:5], s[14:15], v4, s67, v[2:3]
	v_mad_i64_i32 v[6:7], s[14:15], v6, s67, v[2:3]
	global_load_dwordx4 v[46:49], v[4:5], off
	global_load_dwordx4 v[42:45], v[6:7], off
	v_or_b32_e32 v4, 24, v74
	v_or_b32_e32 v6, 28, v74
	v_mad_i64_i32 v[4:5], s[14:15], v4, s67, v[2:3]
	v_mad_i64_i32 v[6:7], s[14:15], v6, s67, v[2:3]
	global_load_dwordx4 v[38:41], v[4:5], off
	global_load_dwordx4 v[34:37], v[6:7], off
	v_or_b32_e32 v4, 32, v74
	v_or_b32_e32 v6, 36, v74
	v_mad_i64_i32 v[4:5], s[14:15], v4, s67, v[2:3]
	v_mad_i64_i32 v[6:7], s[14:15], v6, s67, v[2:3]
	global_load_dwordx4 v[30:33], v[4:5], off
	global_load_dwordx4 v[26:29], v[6:7], off
	v_or_b32_e32 v4, 40, v74
	v_or_b32_e32 v6, 44, v74
	v_mad_i64_i32 v[4:5], s[14:15], v4, s67, v[2:3]
	v_mad_i64_i32 v[6:7], s[14:15], v6, s67, v[2:3]
	global_load_dwordx4 v[22:25], v[4:5], off
	global_load_dwordx4 v[18:21], v[6:7], off
	v_or_b32_e32 v4, 48, v74
	v_or_b32_e32 v6, 52, v74
	v_mad_i64_i32 v[4:5], s[14:15], v4, s67, v[2:3]
	v_mad_i64_i32 v[6:7], s[14:15], v6, s67, v[2:3]
	global_load_dwordx4 v[14:17], v[4:5], off
	global_load_dwordx4 v[10:13], v[6:7], off
	v_or_b32_e32 v4, 56, v74
	v_or_b32_e32 v6, 60, v74
	v_mad_i64_i32 v[4:5], s[14:15], v4, s67, v[2:3]
	v_mad_i64_i32 v[2:3], s[14:15], v6, s67, v[2:3]
	global_load_dwordx4 v[6:9], v[4:5], off
	s_nop 0
	global_load_dwordx4 v[2:5], v[2:3], off
	v_cndmask_b32_e64 v75, 0, 1, s[24:25]
	v_cmp_ne_u32_e64 s[34:35], 1, v75
	s_andn2_b64 vcc, exec, s[24:25]
	s_cbranch_vccnz .LBB0_976
	v_ashrrev_i32_e32 v75, 31, v74
	v_lshl_add_u64 v[74:75], v[74:75], 2, s[2:3]
	global_load_dword v122, v[74:75], off
	global_load_dword v123, v[74:75], off offset:16
	global_load_dword v124, v[74:75], off offset:32
	global_load_dword v125, v[74:75], off offset:48
	global_load_dword v126, v[74:75], off offset:64
	global_load_dword v127, v[74:75], off offset:80
	global_load_dword v128, v[74:75], off offset:96
	global_load_dword v129, v[74:75], off offset:112
	global_load_dword v130, v[74:75], off offset:128
	global_load_dword v131, v[74:75], off offset:144
	global_load_dword v132, v[74:75], off offset:160
	global_load_dword v133, v[74:75], off offset:176
	global_load_dword v134, v[74:75], off offset:192
	global_load_dword v135, v[74:75], off offset:208
	global_load_dword v136, v[74:75], off offset:224
	global_load_dword v137, v[74:75], off offset:240
	s_ashr_i32 s11, s10, 31
	s_waitcnt vmcnt(0)
	v_mov_b32_e32 v74, v122
	v_pk_mul_f32 v[92:93], v[62:63], v[74:75] op_sel_hi:[1,0]
	v_pk_mul_f32 v[74:75], v[64:65], v[74:75] op_sel_hi:[1,0]
	ds_write2_b32 v87, v74, v75 offset0:2 offset1:3
	v_lshl_add_u64 v[74:75], s[10:11], 0, v[66:67]
	v_lshl_add_u64 v[74:75], v[74:75], 2, s[2:3]
	v_mov_b32_e32 v74, v123
	ds_write2_b32 v87, v92, v93 offset1:1
	s_cbranch_execnz .LBB0_956

.LBB0_956:
	s_waitcnt vmcnt(0)
	v_pk_mul_f32 v[58:59], v[58:59], v[74:75] op_sel_hi:[1,0]
	ds_write2_b32 v85, v58, v59 offset1:1
	v_pk_mul_f32 v[58:59], v[60:61], v[74:75] op_sel_hi:[1,0]
	s_and_b64 vcc, exec, s[34:35]
	ds_write2_b32 v85, v58, v59 offset0:2 offset1:3
	s_cbranch_vccnz .LBB0_977
	s_ashr_i32 s11, s10, 31
	v_lshl_add_u64 v[58:59], s[10:11], 0, v[66:67]
	v_lshl_add_u64 v[58:59], v[58:59], 2, s[2:3]
	v_mov_b32_e32 v60, v124
	s_nop 0
	v_mov_b32_e32 v58, v125
	s_waitcnt vmcnt(1)
	v_pk_mul_f32 v[62:63], v[54:55], v[60:61] op_sel_hi:[1,0]
	v_pk_mul_f32 v[60:61], v[56:57], v[60:61] op_sel_hi:[1,0]
	ds_write2_b32 v88, v62, v63 offset1:1
	ds_write2_b32 v88, v60, v61 offset0:2 offset1:3
	s_cbranch_execnz .LBB0_959

.LBB0_959:
	s_waitcnt vmcnt(0)
	v_pk_mul_f32 v[50:51], v[50:51], v[58:59] op_sel_hi:[1,0]
	ds_write2_b32 v86, v50, v51 offset1:1
	v_pk_mul_f32 v[50:51], v[52:53], v[58:59] op_sel_hi:[1,0]
	s_and_b64 vcc, exec, s[34:35]
	ds_write2_b32 v86, v50, v51 offset0:2 offset1:3
	s_cbranch_vccnz .LBB0_978
	s_ashr_i32 s11, s10, 31
	v_lshl_add_u64 v[50:51], s[10:11], 0, v[66:67]
	v_lshl_add_u64 v[50:51], v[50:51], 2, s[2:3]
	v_mov_b32_e32 v52, v126
	s_nop 0
	v_mov_b32_e32 v50, v127
	s_waitcnt vmcnt(1)
	v_pk_mul_f32 v[54:55], v[46:47], v[52:53] op_sel_hi:[1,0]
	v_pk_mul_f32 v[52:53], v[48:49], v[52:53] op_sel_hi:[1,0]
	ds_write2_b32 v89, v54, v55 offset1:1
	ds_write2_b32 v89, v52, v53 offset0:2 offset1:3
	s_cbranch_execnz .LBB0_962

.LBB0_962:
	s_waitcnt vmcnt(0)
	v_pk_mul_f32 v[42:43], v[42:43], v[50:51] op_sel_hi:[1,0]
	v_add_u32_e32 v46, 0x410, v89
	ds_write2_b32 v46, v42, v43 offset1:1
	v_pk_mul_f32 v[42:43], v[44:45], v[50:51] op_sel_hi:[1,0]
	v_add_u32_e32 v44, 0x418, v89
	ds_write2_b32 v44, v42, v43 offset1:1
	s_and_b64 vcc, exec, s[34:35]
	v_add_u32_e32 v43, 0x820, v89
	v_add_u32_e32 v44, 0x828, v89
	s_cbranch_vccnz .LBB0_979
	s_ashr_i32 s11, s10, 31
	v_lshl_add_u64 v[46:47], s[10:11], 0, v[66:67]
	v_lshl_add_u64 v[46:47], v[46:47], 2, s[2:3]
	v_mov_b32_e32 v42, v128
	s_waitcnt vmcnt(0)
	v_pk_mul_f32 v[48:49], v[38:39], v[42:43] op_sel_hi:[1,0]
	ds_write2_b32 v43, v48, v49 offset1:1
	v_pk_mul_f32 v[48:49], v[40:41], v[42:43] op_sel_hi:[1,0]
	v_mov_b32_e32 v42, v129
	ds_write2_b32 v44, v48, v49 offset1:1
	s_cbranch_execnz .LBB0_965

.LBB0_965:
	s_waitcnt vmcnt(0)
	v_pk_mul_f32 v[34:35], v[34:35], v[42:43] op_sel_hi:[1,0]
	v_add_u32_e32 v38, 0xc30, v89
	ds_write2_b32 v38, v34, v35 offset1:1
	v_pk_mul_f32 v[34:35], v[36:37], v[42:43] op_sel_hi:[1,0]
	v_add_u32_e32 v36, 0xc38, v89
	ds_write2_b32 v36, v34, v35 offset1:1
	s_and_b64 vcc, exec, s[34:35]
	v_add_u32_e32 v35, 0x1040, v89
	v_add_u32_e32 v36, 0x1048, v89
	s_cbranch_vccnz .LBB0_980
	s_ashr_i32 s11, s10, 31
	v_lshl_add_u64 v[38:39], s[10:11], 0, v[66:67]
	v_lshl_add_u64 v[38:39], v[38:39], 2, s[2:3]
	v_mov_b32_e32 v34, v130
	s_waitcnt vmcnt(0)
	v_pk_mul_f32 v[40:41], v[30:31], v[34:35] op_sel_hi:[1,0]
	ds_write2_b32 v35, v40, v41 offset1:1
	v_pk_mul_f32 v[40:41], v[32:33], v[34:35] op_sel_hi:[1,0]
	v_mov_b32_e32 v34, v131
	ds_write2_b32 v36, v40, v41 offset1:1
	s_cbranch_execnz .LBB0_968

.LBB0_968:
	s_waitcnt vmcnt(0)
	v_pk_mul_f32 v[26:27], v[26:27], v[34:35] op_sel_hi:[1,0]
	v_add_u32_e32 v30, 0x1450, v89
	ds_write2_b32 v30, v26, v27 offset1:1
	v_pk_mul_f32 v[26:27], v[28:29], v[34:35] op_sel_hi:[1,0]
	v_add_u32_e32 v28, 0x1458, v89
	ds_write2_b32 v28, v26, v27 offset1:1
	s_and_b64 vcc, exec, s[34:35]
	v_add_u32_e32 v27, 0x1860, v89
	v_add_u32_e32 v28, 0x1868, v89
	s_cbranch_vccnz .LBB0_981
	s_ashr_i32 s11, s10, 31
	v_lshl_add_u64 v[30:31], s[10:11], 0, v[66:67]
	v_lshl_add_u64 v[30:31], v[30:31], 2, s[2:3]
	v_mov_b32_e32 v26, v132
	s_waitcnt vmcnt(0)
	v_pk_mul_f32 v[32:33], v[22:23], v[26:27] op_sel_hi:[1,0]
	ds_write2_b32 v27, v32, v33 offset1:1
	v_pk_mul_f32 v[32:33], v[24:25], v[26:27] op_sel_hi:[1,0]
	v_mov_b32_e32 v26, v133
	ds_write2_b32 v28, v32, v33 offset1:1
	s_cbranch_execnz .LBB0_971

.LBB0_971:
	s_waitcnt vmcnt(0)
	v_pk_mul_f32 v[18:19], v[18:19], v[26:27] op_sel_hi:[1,0]
	v_add_u32_e32 v22, 0x1c70, v89
	ds_write2_b32 v22, v18, v19 offset1:1
	v_pk_mul_f32 v[18:19], v[20:21], v[26:27] op_sel_hi:[1,0]
	v_add_u32_e32 v20, 0x1c78, v89
	ds_write2_b32 v20, v18, v19 offset1:1
	s_and_b64 vcc, exec, s[34:35]
	v_add_u32_e32 v19, 0x2080, v89
	v_add_u32_e32 v20, 0x2088, v89
	s_cbranch_vccnz .LBB0_982
	s_ashr_i32 s11, s10, 31
	v_lshl_add_u64 v[22:23], s[10:11], 0, v[66:67]
	v_lshl_add_u64 v[22:23], v[22:23], 2, s[2:3]
	v_mov_b32_e32 v18, v134
	s_waitcnt vmcnt(0)
	v_pk_mul_f32 v[24:25], v[14:15], v[18:19] op_sel_hi:[1,0]
	ds_write2_b32 v19, v24, v25 offset1:1
	v_pk_mul_f32 v[24:25], v[16:17], v[18:19] op_sel_hi:[1,0]
	v_mov_b32_e32 v18, v135
	ds_write2_b32 v20, v24, v25 offset1:1
	s_cbranch_execnz .LBB0_974

.LBB0_974:
	s_waitcnt vmcnt(0)
	v_pk_mul_f32 v[10:11], v[10:11], v[18:19] op_sel_hi:[1,0]
	v_add_u32_e32 v14, 0x2490, v89
	ds_write2_b32 v14, v10, v11 offset1:1
	v_pk_mul_f32 v[10:11], v[12:13], v[18:19] op_sel_hi:[1,0]
	v_add_u32_e32 v12, 0x2498, v89
	ds_write2_b32 v12, v10, v11 offset1:1
	s_and_b64 vcc, exec, s[34:35]
	v_add_u32_e32 v11, 0x28a0, v89
	v_add_u32_e32 v12, 0x28a8, v89
	s_cbranch_vccnz .LBB0_983
	s_ashr_i32 s11, s10, 31
	v_lshl_add_u64 v[14:15], s[10:11], 0, v[66:67]
	v_lshl_add_u64 v[14:15], v[14:15], 2, s[2:3]
	v_mov_b32_e32 v10, v136
	s_waitcnt vmcnt(0)
	v_pk_mul_f32 v[16:17], v[6:7], v[10:11] op_sel_hi:[1,0]
	ds_write2_b32 v11, v16, v17 offset1:1
	v_pk_mul_f32 v[16:17], v[8:9], v[10:11] op_sel_hi:[1,0]
	v_mov_b32_e32 v10, v137
	ds_write2_b32 v12, v16, v17 offset1:1
	s_cbranch_execnz .LBB0_948
	s_branch .LBB0_947

.LBB0_997:
	s_andn2_b64 vcc, exec, s[10:11]
	s_cbranch_vccnz .LBB0_994
	s_mul_hi_i32 s0, s27, 0x2e8ba2e9
	s_lshr_b32 s10, s0, 31
	s_ashr_i32 s0, s0, 4
	s_add_i32 s10, s0, s10
	s_mul_i32 s0, s10, 0xffffffa8
	s_add_i32 s11, s27, s0
	s_mul_i32 s0, s11, 47
	s_sext_i32_i16 s12, s0
	s_ashr_i32 s12, s12, 11
	s_bfe_u32 s0, s0, 0x1000f
	s_add_i32 s0, s12, s0
	s_mul_i32 s12, s0, 44
	s_sub_i32 s12, s11, s12
	s_sext_i32_i8 s30, s12
	s_lshl_b32 s12, s30, 6
	s_add_i32 s11, s11, 43
	s_cmpk_lt_u32 s11, 0x57
	s_cselect_b32 s13, s74, s76
	s_mul_i32 s14, s16, 0xb00000
	s_cselect_b32 s11, s75, s77
	s_add_u32 s31, s13, s14
	s_mul_hi_u32 s13, s16, 0xb00000
	s_addc_u32 s11, s11, s13
	s_ashr_i32 s13, s12, 31
	s_lshl_b32 s10, s10, 6
	s_lshl_b64 s[14:15], s[12:13], 2
	s_add_u32 s14, s31, s14
	v_or_b32_e32 v80, s10, v66
	s_addc_u32 s15, s11, s15
	v_lshl_add_u64 v[2:3], s[14:15], 0, v[0:1]
	v_or_b32_e32 v6, 4, v80
	v_mad_i64_i32 v[4:5], s[14:15], v80, s67, v[2:3]
	v_mad_i64_i32 v[6:7], s[14:15], v6, s67, v[2:3]
	global_load_dwordx4 v[62:65], v[4:5], off
	global_load_dwordx4 v[58:61], v[6:7], off
	v_or_b32_e32 v4, 8, v80
	v_or_b32_e32 v6, 12, v80
	v_mad_i64_i32 v[4:5], s[14:15], v4, s67, v[2:3]
	v_mad_i64_i32 v[6:7], s[14:15], v6, s67, v[2:3]
	global_load_dwordx4 v[54:57], v[4:5], off
	global_load_dwordx4 v[50:53], v[6:7], off
	v_or_b32_e32 v4, 16, v80
	v_or_b32_e32 v6, 20, v80
	v_mad_i64_i32 v[4:5], s[14:15], v4, s67, v[2:3]
	v_mad_i64_i32 v[6:7], s[14:15], v6, s67, v[2:3]
	global_load_dwordx4 v[46:49], v[4:5], off
	global_load_dwordx4 v[42:45], v[6:7], off
	v_or_b32_e32 v4, 24, v80
	v_or_b32_e32 v6, 28, v80
	v_mad_i64_i32 v[4:5], s[14:15], v4, s67, v[2:3]
	v_mad_i64_i32 v[6:7], s[14:15], v6, s67, v[2:3]
	global_load_dwordx4 v[38:41], v[4:5], off
	global_load_dwordx4 v[34:37], v[6:7], off
	v_or_b32_e32 v4, 32, v80
	v_or_b32_e32 v6, 36, v80
	v_mad_i64_i32 v[4:5], s[14:15], v4, s67, v[2:3]
	v_mad_i64_i32 v[6:7], s[14:15], v6, s67, v[2:3]
	global_load_dwordx4 v[30:33], v[4:5], off
	global_load_dwordx4 v[26:29], v[6:7], off
	v_or_b32_e32 v4, 40, v80
	v_or_b32_e32 v6, 44, v80
	v_mad_i64_i32 v[4:5], s[14:15], v4, s67, v[2:3]
	v_mad_i64_i32 v[6:7], s[14:15], v6, s67, v[2:3]
	global_load_dwordx4 v[22:25], v[4:5], off
	global_load_dwordx4 v[18:21], v[6:7], off
	v_or_b32_e32 v4, 48, v80
	v_or_b32_e32 v6, 52, v80
	v_mad_i64_i32 v[4:5], s[14:15], v4, s67, v[2:3]
	v_mad_i64_i32 v[6:7], s[14:15], v6, s67, v[2:3]
	global_load_dwordx4 v[14:17], v[4:5], off
	global_load_dwordx4 v[10:13], v[6:7], off
	v_or_b32_e32 v4, 56, v80
	v_or_b32_e32 v6, 60, v80
	v_mad_i64_i32 v[4:5], s[14:15], v4, s67, v[2:3]
	v_mad_i64_i32 v[2:3], s[14:15], v6, s67, v[2:3]
	global_load_dwordx4 v[6:9], v[4:5], off
	s_nop 0
	global_load_dwordx4 v[2:5], v[2:3], off
	v_cndmask_b32_e64 v81, 0, 1, s[24:25]
	v_cmp_ne_u32_e64 s[36:37], 1, v81
	s_andn2_b64 vcc, exec, s[24:25]
	v_add_u32_e32 v97, v82, v83
	s_cbranch_vccnz .LBB0_1021
	v_ashrrev_i32_e32 v81, 31, v80
	v_lshl_add_u64 v[80:81], v[80:81], 2, s[8:9]
	s_ashr_i32 s11, s10, 31
	global_load_dword v122, v[80:81], off
	global_load_dword v123, v[80:81], off offset:16
	global_load_dword v124, v[80:81], off offset:32
	global_load_dword v125, v[80:81], off offset:48
	global_load_dword v126, v[80:81], off offset:64
	global_load_dword v127, v[80:81], off offset:80
	global_load_dword v128, v[80:81], off offset:96
	global_load_dword v129, v[80:81], off offset:112
	global_load_dword v130, v[80:81], off offset:128
	global_load_dword v131, v[80:81], off offset:144
	global_load_dword v132, v[80:81], off offset:160
	global_load_dword v133, v[80:81], off offset:176
	global_load_dword v134, v[80:81], off offset:192
	global_load_dword v135, v[80:81], off offset:208
	global_load_dword v136, v[80:81], off offset:224
	global_load_dword v137, v[80:81], off offset:240
	v_lshl_add_u64 v[80:81], s[10:11], 0, v[66:67]
	v_lshl_add_u64 v[80:81], v[80:81], 2, s[8:9]
	s_waitcnt vmcnt(0)
	v_mov_b32_e32 v98, v122
	v_mov_b32_e32 v80, v123
	v_pk_mul_f32 v[100:101], v[62:63], v[98:99] op_sel_hi:[1,0]
	v_pk_mul_f32 v[98:99], v[64:65], v[98:99] op_sel_hi:[1,0]
	ds_write2_b32 v97, v100, v101 offset1:1
	ds_write2_b32 v97, v98, v99 offset0:2 offset1:3
	s_cbranch_execnz .LBB0_1001

.LBB0_1001:
	s_waitcnt vmcnt(0)
	v_pk_mul_f32 v[58:59], v[58:59], v[80:81] op_sel_hi:[1,0]
	ds_write2_b32 v93, v58, v59 offset1:1
	v_pk_mul_f32 v[58:59], v[60:61], v[80:81] op_sel_hi:[1,0]
	s_and_b64 vcc, exec, s[36:37]
	ds_write2_b32 v93, v58, v59 offset0:2 offset1:3
	s_cbranch_vccnz .LBB0_1022
	s_ashr_i32 s11, s10, 31
	v_lshl_add_u64 v[58:59], s[10:11], 0, v[66:67]
	v_lshl_add_u64 v[58:59], v[58:59], 2, s[8:9]
	v_mov_b32_e32 v60, v124
	s_nop 0
	v_mov_b32_e32 v58, v125
	s_waitcnt vmcnt(1)
	v_pk_mul_f32 v[62:63], v[54:55], v[60:61] op_sel_hi:[1,0]
	v_pk_mul_f32 v[60:61], v[56:57], v[60:61] op_sel_hi:[1,0]
	ds_write2_b32 v95, v62, v63 offset1:1
	ds_write2_b32 v95, v60, v61 offset0:2 offset1:3
	s_cbranch_execnz .LBB0_1004

.LBB0_1004:
	s_waitcnt vmcnt(0)
	v_pk_mul_f32 v[50:51], v[50:51], v[58:59] op_sel_hi:[1,0]
	ds_write2_b32 v94, v50, v51 offset1:1
	v_pk_mul_f32 v[50:51], v[52:53], v[58:59] op_sel_hi:[1,0]
	s_and_b64 vcc, exec, s[36:37]
	ds_write2_b32 v94, v50, v51 offset0:2 offset1:3
	s_cbranch_vccnz .LBB0_1023
	s_ashr_i32 s11, s10, 31
	v_lshl_add_u64 v[50:51], s[10:11], 0, v[66:67]
	v_lshl_add_u64 v[50:51], v[50:51], 2, s[8:9]
	v_mov_b32_e32 v52, v126
	s_nop 0
	v_mov_b32_e32 v50, v127
	s_waitcnt vmcnt(1)
	v_pk_mul_f32 v[54:55], v[46:47], v[52:53] op_sel_hi:[1,0]
	v_pk_mul_f32 v[52:53], v[48:49], v[52:53] op_sel_hi:[1,0]
	ds_write2_b32 v96, v54, v55 offset1:1
	ds_write2_b32 v96, v52, v53 offset0:2 offset1:3
	s_cbranch_execnz .LBB0_1007

.LBB0_1007:
	s_waitcnt vmcnt(0)
	v_pk_mul_f32 v[42:43], v[42:43], v[50:51] op_sel_hi:[1,0]
	v_add_u32_e32 v46, 0x410, v96
	ds_write2_b32 v46, v42, v43 offset1:1
	v_pk_mul_f32 v[42:43], v[44:45], v[50:51] op_sel_hi:[1,0]
	v_add_u32_e32 v44, 0x418, v96
	ds_write2_b32 v44, v42, v43 offset1:1
	s_and_b64 vcc, exec, s[36:37]
	v_add_u32_e32 v43, 0x820, v96
	v_add_u32_e32 v44, 0x828, v96
	s_cbranch_vccnz .LBB0_1024
	s_ashr_i32 s11, s10, 31
	v_lshl_add_u64 v[46:47], s[10:11], 0, v[66:67]
	v_lshl_add_u64 v[46:47], v[46:47], 2, s[8:9]
	v_mov_b32_e32 v48, v128
	v_mov_b32_e32 v42, v129
	s_waitcnt vmcnt(1)
	v_pk_mul_f32 v[46:47], v[38:39], v[48:49] op_sel_hi:[1,0]
	v_pk_mul_f32 v[48:49], v[40:41], v[48:49] op_sel_hi:[1,0]
	ds_write2_b32 v43, v46, v47 offset1:1
	ds_write2_b32 v44, v48, v49 offset1:1
	s_cbranch_execnz .LBB0_1010

.LBB0_1010:
	s_waitcnt vmcnt(0)
	v_pk_mul_f32 v[34:35], v[34:35], v[42:43] op_sel_hi:[1,0]
	v_add_u32_e32 v38, 0xc30, v96
	ds_write2_b32 v38, v34, v35 offset1:1
	v_pk_mul_f32 v[34:35], v[36:37], v[42:43] op_sel_hi:[1,0]
	v_add_u32_e32 v36, 0xc38, v96
	ds_write2_b32 v36, v34, v35 offset1:1
	s_and_b64 vcc, exec, s[36:37]
	v_add_u32_e32 v35, 0x1040, v96
	v_add_u32_e32 v36, 0x1048, v96
	s_cbranch_vccnz .LBB0_1025
	s_ashr_i32 s11, s10, 31
	v_lshl_add_u64 v[38:39], s[10:11], 0, v[66:67]
	v_lshl_add_u64 v[38:39], v[38:39], 2, s[8:9]
	v_mov_b32_e32 v40, v130
	v_mov_b32_e32 v34, v131
	s_waitcnt vmcnt(1)
	v_pk_mul_f32 v[38:39], v[30:31], v[40:41] op_sel_hi:[1,0]
	v_pk_mul_f32 v[40:41], v[32:33], v[40:41] op_sel_hi:[1,0]
	ds_write2_b32 v35, v38, v39 offset1:1
	ds_write2_b32 v36, v40, v41 offset1:1
	s_cbranch_execnz .LBB0_1013

.LBB0_1013:
	s_waitcnt vmcnt(0)
	v_pk_mul_f32 v[26:27], v[26:27], v[34:35] op_sel_hi:[1,0]
	v_add_u32_e32 v30, 0x1450, v96
	ds_write2_b32 v30, v26, v27 offset1:1
	v_pk_mul_f32 v[26:27], v[28:29], v[34:35] op_sel_hi:[1,0]
	v_add_u32_e32 v28, 0x1458, v96
	ds_write2_b32 v28, v26, v27 offset1:1
	s_and_b64 vcc, exec, s[36:37]
	v_add_u32_e32 v27, 0x1860, v96
	v_add_u32_e32 v28, 0x1868, v96
	s_cbranch_vccnz .LBB0_1026
	s_ashr_i32 s11, s10, 31
	v_lshl_add_u64 v[30:31], s[10:11], 0, v[66:67]
	v_lshl_add_u64 v[30:31], v[30:31], 2, s[8:9]
	v_mov_b32_e32 v32, v132
	v_mov_b32_e32 v26, v133
	s_waitcnt vmcnt(1)
	v_pk_mul_f32 v[30:31], v[22:23], v[32:33] op_sel_hi:[1,0]
	v_pk_mul_f32 v[32:33], v[24:25], v[32:33] op_sel_hi:[1,0]
	ds_write2_b32 v27, v30, v31 offset1:1
	ds_write2_b32 v28, v32, v33 offset1:1
	s_cbranch_execnz .LBB0_1016

.LBB0_1016:
	s_waitcnt vmcnt(0)
	v_pk_mul_f32 v[18:19], v[18:19], v[26:27] op_sel_hi:[1,0]
	v_add_u32_e32 v22, 0x1c70, v96
	ds_write2_b32 v22, v18, v19 offset1:1
	v_pk_mul_f32 v[18:19], v[20:21], v[26:27] op_sel_hi:[1,0]
	v_add_u32_e32 v20, 0x1c78, v96
	ds_write2_b32 v20, v18, v19 offset1:1
	s_and_b64 vcc, exec, s[36:37]
	v_add_u32_e32 v19, 0x2080, v96
	v_add_u32_e32 v20, 0x2088, v96
	s_cbranch_vccnz .LBB0_1027
	s_ashr_i32 s11, s10, 31
	v_lshl_add_u64 v[22:23], s[10:11], 0, v[66:67]
	v_lshl_add_u64 v[22:23], v[22:23], 2, s[8:9]
	v_mov_b32_e32 v24, v134
	v_mov_b32_e32 v18, v135
	s_waitcnt vmcnt(1)
	v_pk_mul_f32 v[22:23], v[14:15], v[24:25] op_sel_hi:[1,0]
	v_pk_mul_f32 v[24:25], v[16:17], v[24:25] op_sel_hi:[1,0]
	ds_write2_b32 v19, v22, v23 offset1:1
	ds_write2_b32 v20, v24, v25 offset1:1
	s_cbranch_execnz .LBB0_1019

.LBB0_1019:
	s_waitcnt vmcnt(0)
	v_pk_mul_f32 v[10:11], v[10:11], v[18:19] op_sel_hi:[1,0]
	v_add_u32_e32 v14, 0x2490, v96
	ds_write2_b32 v14, v10, v11 offset1:1
	v_pk_mul_f32 v[10:11], v[12:13], v[18:19] op_sel_hi:[1,0]
	v_add_u32_e32 v12, 0x2498, v96
	ds_write2_b32 v12, v10, v11 offset1:1
	s_and_b64 vcc, exec, s[36:37]
	v_add_u32_e32 v11, 0x28a0, v96
	v_add_u32_e32 v12, 0x28a8, v96
	s_cbranch_vccnz .LBB0_1028
	s_ashr_i32 s11, s10, 31
	v_lshl_add_u64 v[14:15], s[10:11], 0, v[66:67]
	v_lshl_add_u64 v[14:15], v[14:15], 2, s[8:9]
	v_mov_b32_e32 v16, v136
	v_mov_b32_e32 v10, v137
	s_waitcnt vmcnt(1)
	v_pk_mul_f32 v[14:15], v[6:7], v[16:17] op_sel_hi:[1,0]
	v_pk_mul_f32 v[16:17], v[8:9], v[16:17] op_sel_hi:[1,0]
	ds_write2_b32 v11, v14, v15 offset1:1
	ds_write2_b32 v12, v16, v17 offset1:1
	s_cbranch_execnz .LBB0_993
	s_branch .LBB0_992

.LBB0_1035:
	s_mul_hi_i32 s6, s0, 0x2e8ba2e9
	s_lshr_b32 s7, s6, 31
	s_ashr_i32 s6, s6, 4
	s_add_i32 s6, s6, s7
	s_mul_i32 s7, s6, 0xffffffa8
	s_add_i32 s7, s0, s7
	s_mul_i32 s8, s7, 47
	s_sext_i32_i16 s9, s8
	s_ashr_i32 s12, s9, 11
	s_bfe_u32 s8, s8, 0x1000f
	s_add_i32 s12, s12, s8
	s_mul_i32 s8, s12, 44
	s_sub_i32 s8, s7, s8
	s_sext_i32_i8 s13, s8
	s_lshl_b32 s8, s13, 6
	s_add_i32 s7, s7, 43
	s_cmpk_lt_u32 s7, 0x57
	s_cselect_b32 s7, s75, s77
	s_cselect_b32 s14, s74, s76
	s_ashr_i32 s9, s8, 31
	s_lshl_b32 s6, s6, 6
	s_lshl_b64 s[10:11], s[8:9], 2
	s_add_u32 s10, s14, s10
	v_or_b32_e32 v70, s6, v66
	s_addc_u32 s11, s7, s11
	v_lshl_add_u64 v[2:3], s[10:11], 0, v[0:1]
	v_or_b32_e32 v6, 4, v70
	v_mad_i64_i32 v[4:5], s[10:11], v70, s67, v[2:3]
	v_mad_i64_i32 v[6:7], s[10:11], v6, s67, v[2:3]
	global_load_dwordx4 v[62:65], v[4:5], off
	global_load_dwordx4 v[58:61], v[6:7], off
	v_or_b32_e32 v4, 8, v70
	v_or_b32_e32 v6, 12, v70
	v_mad_i64_i32 v[4:5], s[10:11], v4, s67, v[2:3]
	v_mad_i64_i32 v[6:7], s[10:11], v6, s67, v[2:3]
	global_load_dwordx4 v[54:57], v[4:5], off
	global_load_dwordx4 v[50:53], v[6:7], off
	v_or_b32_e32 v4, 16, v70
	v_or_b32_e32 v6, 20, v70
	v_mad_i64_i32 v[4:5], s[10:11], v4, s67, v[2:3]
	v_mad_i64_i32 v[6:7], s[10:11], v6, s67, v[2:3]
	global_load_dwordx4 v[46:49], v[4:5], off
	global_load_dwordx4 v[42:45], v[6:7], off
	v_or_b32_e32 v4, 24, v70
	v_or_b32_e32 v6, 28, v70
	v_mad_i64_i32 v[4:5], s[10:11], v4, s67, v[2:3]
	v_mad_i64_i32 v[6:7], s[10:11], v6, s67, v[2:3]
	global_load_dwordx4 v[38:41], v[4:5], off
	global_load_dwordx4 v[34:37], v[6:7], off
	v_or_b32_e32 v4, 32, v70
	v_or_b32_e32 v6, 36, v70
	v_mad_i64_i32 v[4:5], s[10:11], v4, s67, v[2:3]
	v_mad_i64_i32 v[6:7], s[10:11], v6, s67, v[2:3]
	global_load_dwordx4 v[30:33], v[4:5], off
	global_load_dwordx4 v[26:29], v[6:7], off
	v_or_b32_e32 v4, 40, v70
	v_or_b32_e32 v6, 44, v70
	v_mad_i64_i32 v[4:5], s[10:11], v4, s67, v[2:3]
	v_mad_i64_i32 v[6:7], s[10:11], v6, s67, v[2:3]
	global_load_dwordx4 v[22:25], v[4:5], off
	global_load_dwordx4 v[18:21], v[6:7], off
	v_or_b32_e32 v4, 48, v70
	v_or_b32_e32 v6, 52, v70
	v_or_b32_e32 v8, 56, v70
	v_or_b32_e32 v10, 60, v70
	v_mad_i64_i32 v[4:5], s[10:11], v4, s67, v[2:3]
	v_mad_i64_i32 v[6:7], s[10:11], v6, s67, v[2:3]
	v_mad_i64_i32 v[8:9], s[10:11], v8, s67, v[2:3]
	v_mad_i64_i32 v[2:3], s[10:11], v10, s67, v[2:3]
	global_load_dwordx4 v[14:17], v[4:5], off
	global_load_dwordx4 v[10:13], v[6:7], off
	s_nop 0
	global_load_dwordx4 v[6:9], v[8:9], off
	s_nop 0
	global_load_dwordx4 v[2:5], v[2:3], off
	v_cndmask_b32_e64 v71, 0, 1, s[24:25]
	v_cmp_ne_u32_e64 s[36:37], 1, v71
	s_andn2_b64 vcc, exec, s[24:25]
	s_cbranch_vccnz .LBB0_1058
	v_ashrrev_i32_e32 v71, 31, v70
	v_lshl_add_u64 v[70:71], v[70:71], 2, s[72:73]
	s_ashr_i32 s7, s6, 31
	global_load_dword v122, v[70:71], off
	global_load_dword v123, v[70:71], off offset:16
	global_load_dword v124, v[70:71], off offset:32
	global_load_dword v125, v[70:71], off offset:48
	global_load_dword v126, v[70:71], off offset:64
	global_load_dword v127, v[70:71], off offset:80
	global_load_dword v128, v[70:71], off offset:96
	global_load_dword v129, v[70:71], off offset:112
	global_load_dword v130, v[70:71], off offset:128
	global_load_dword v131, v[70:71], off offset:144
	global_load_dword v132, v[70:71], off offset:160
	global_load_dword v133, v[70:71], off offset:176
	global_load_dword v134, v[70:71], off offset:192
	global_load_dword v135, v[70:71], off offset:208
	global_load_dword v136, v[70:71], off offset:224
	global_load_dword v137, v[70:71], off offset:240
	v_lshl_add_u64 v[70:71], s[6:7], 0, v[66:67]
	v_lshl_add_u64 v[70:71], v[70:71], 2, s[72:73]
	s_waitcnt vmcnt(0)
	v_mov_b32_e32 v86, v122
	v_mov_b32_e32 v70, v123
	v_pk_mul_f32 v[88:89], v[62:63], v[86:87] op_sel_hi:[1,0]
	v_pk_mul_f32 v[86:87], v[64:65], v[86:87] op_sel_hi:[1,0]
	ds_write2_b32 v83, v88, v89 offset1:1
	ds_write2_b32 v83, v86, v87 offset0:2 offset1:3
	s_cbranch_execnz .LBB0_1038

.LBB0_1038:
	s_waitcnt vmcnt(0)
	v_pk_mul_f32 v[58:59], v[58:59], v[70:71] op_sel_hi:[1,0]
	ds_write2_b32 v81, v58, v59 offset1:1
	v_pk_mul_f32 v[58:59], v[60:61], v[70:71] op_sel_hi:[1,0]
	s_and_b64 vcc, exec, s[36:37]
	ds_write2_b32 v81, v58, v59 offset0:2 offset1:3
	s_cbranch_vccnz .LBB0_1059
	s_ashr_i32 s7, s6, 31
	v_lshl_add_u64 v[58:59], s[6:7], 0, v[66:67]
	v_lshl_add_u64 v[58:59], v[58:59], 2, s[72:73]
	v_mov_b32_e32 v60, v124
	s_nop 0
	v_mov_b32_e32 v58, v125
	s_waitcnt vmcnt(1)
	v_pk_mul_f32 v[62:63], v[54:55], v[60:61] op_sel_hi:[1,0]
	v_pk_mul_f32 v[60:61], v[56:57], v[60:61] op_sel_hi:[1,0]
	ds_write2_b32 v84, v62, v63 offset1:1
	ds_write2_b32 v84, v60, v61 offset0:2 offset1:3
	s_cbranch_execnz .LBB0_1041

.LBB0_1041:
	s_waitcnt vmcnt(0)
	v_pk_mul_f32 v[50:51], v[50:51], v[58:59] op_sel_hi:[1,0]
	ds_write2_b32 v82, v50, v51 offset1:1
	v_pk_mul_f32 v[50:51], v[52:53], v[58:59] op_sel_hi:[1,0]
	s_and_b64 vcc, exec, s[36:37]
	ds_write2_b32 v82, v50, v51 offset0:2 offset1:3
	s_cbranch_vccnz .LBB0_1060
	s_ashr_i32 s7, s6, 31
	v_lshl_add_u64 v[50:51], s[6:7], 0, v[66:67]
	v_lshl_add_u64 v[50:51], v[50:51], 2, s[72:73]
	v_mov_b32_e32 v52, v126
	s_nop 0
	v_mov_b32_e32 v50, v127
	s_waitcnt vmcnt(1)
	v_pk_mul_f32 v[54:55], v[46:47], v[52:53] op_sel_hi:[1,0]
	v_pk_mul_f32 v[52:53], v[48:49], v[52:53] op_sel_hi:[1,0]
	ds_write2_b32 v85, v54, v55 offset1:1
	ds_write2_b32 v85, v52, v53 offset0:2 offset1:3
	s_cbranch_execnz .LBB0_1044

.LBB0_1044:
	s_waitcnt vmcnt(0)
	v_pk_mul_f32 v[42:43], v[42:43], v[50:51] op_sel_hi:[1,0]
	v_add_u32_e32 v46, 0x410, v85
	ds_write2_b32 v46, v42, v43 offset1:1
	v_pk_mul_f32 v[42:43], v[44:45], v[50:51] op_sel_hi:[1,0]
	v_add_u32_e32 v44, 0x418, v85
	ds_write2_b32 v44, v42, v43 offset1:1
	s_and_b64 vcc, exec, s[36:37]
	v_add_u32_e32 v43, 0x820, v85
	v_add_u32_e32 v44, 0x828, v85
	s_cbranch_vccnz .LBB0_1061
	s_ashr_i32 s7, s6, 31
	v_lshl_add_u64 v[46:47], s[6:7], 0, v[66:67]
	v_lshl_add_u64 v[46:47], v[46:47], 2, s[72:73]
	v_mov_b32_e32 v48, v128
	v_mov_b32_e32 v42, v129
	s_waitcnt vmcnt(1)
	v_pk_mul_f32 v[46:47], v[38:39], v[48:49] op_sel_hi:[1,0]
	v_pk_mul_f32 v[48:49], v[40:41], v[48:49] op_sel_hi:[1,0]
	ds_write2_b32 v43, v46, v47 offset1:1
	ds_write2_b32 v44, v48, v49 offset1:1
	s_cbranch_execnz .LBB0_1047

.LBB0_1047:
	s_waitcnt vmcnt(0)
	v_pk_mul_f32 v[34:35], v[34:35], v[42:43] op_sel_hi:[1,0]
	v_add_u32_e32 v38, 0xc30, v85
	ds_write2_b32 v38, v34, v35 offset1:1
	v_pk_mul_f32 v[34:35], v[36:37], v[42:43] op_sel_hi:[1,0]
	v_add_u32_e32 v36, 0xc38, v85
	ds_write2_b32 v36, v34, v35 offset1:1
	s_and_b64 vcc, exec, s[36:37]
	v_add_u32_e32 v35, 0x1040, v85
	v_add_u32_e32 v36, 0x1048, v85
	s_cbranch_vccnz .LBB0_1062
	s_ashr_i32 s7, s6, 31
	v_lshl_add_u64 v[38:39], s[6:7], 0, v[66:67]
	v_lshl_add_u64 v[38:39], v[38:39], 2, s[72:73]
	v_mov_b32_e32 v40, v130
	v_mov_b32_e32 v34, v131
	s_waitcnt vmcnt(1)
	v_pk_mul_f32 v[38:39], v[30:31], v[40:41] op_sel_hi:[1,0]
	v_pk_mul_f32 v[40:41], v[32:33], v[40:41] op_sel_hi:[1,0]
	ds_write2_b32 v35, v38, v39 offset1:1
	ds_write2_b32 v36, v40, v41 offset1:1
	s_cbranch_execnz .LBB0_1050

.LBB0_1050:
	s_waitcnt vmcnt(0)
	v_pk_mul_f32 v[26:27], v[26:27], v[34:35] op_sel_hi:[1,0]
	v_add_u32_e32 v30, 0x1450, v85
	ds_write2_b32 v30, v26, v27 offset1:1
	v_pk_mul_f32 v[26:27], v[28:29], v[34:35] op_sel_hi:[1,0]
	v_add_u32_e32 v28, 0x1458, v85
	ds_write2_b32 v28, v26, v27 offset1:1
	s_and_b64 vcc, exec, s[36:37]
	v_add_u32_e32 v27, 0x1860, v85
	v_add_u32_e32 v28, 0x1868, v85
	s_cbranch_vccnz .LBB0_1063
	s_ashr_i32 s7, s6, 31
	v_lshl_add_u64 v[30:31], s[6:7], 0, v[66:67]
	v_lshl_add_u64 v[30:31], v[30:31], 2, s[72:73]
	v_mov_b32_e32 v32, v132
	v_mov_b32_e32 v26, v133
	s_waitcnt vmcnt(1)
	v_pk_mul_f32 v[30:31], v[22:23], v[32:33] op_sel_hi:[1,0]
	v_pk_mul_f32 v[32:33], v[24:25], v[32:33] op_sel_hi:[1,0]
	ds_write2_b32 v27, v30, v31 offset1:1
	ds_write2_b32 v28, v32, v33 offset1:1
	s_cbranch_execnz .LBB0_1053

.LBB0_1053:
	s_waitcnt vmcnt(0)
	v_pk_mul_f32 v[18:19], v[18:19], v[26:27] op_sel_hi:[1,0]
	v_add_u32_e32 v22, 0x1c70, v85
	ds_write2_b32 v22, v18, v19 offset1:1
	v_pk_mul_f32 v[18:19], v[20:21], v[26:27] op_sel_hi:[1,0]
	v_add_u32_e32 v20, 0x1c78, v85
	ds_write2_b32 v20, v18, v19 offset1:1
	s_and_b64 vcc, exec, s[36:37]
	v_add_u32_e32 v19, 0x2080, v85
	v_add_u32_e32 v20, 0x2088, v85
	s_cbranch_vccnz .LBB0_1064
	s_ashr_i32 s7, s6, 31
	v_lshl_add_u64 v[22:23], s[6:7], 0, v[66:67]
	v_lshl_add_u64 v[22:23], v[22:23], 2, s[72:73]
	v_mov_b32_e32 v24, v134
	v_mov_b32_e32 v18, v135
	s_waitcnt vmcnt(1)
	v_pk_mul_f32 v[22:23], v[14:15], v[24:25] op_sel_hi:[1,0]
	v_pk_mul_f32 v[24:25], v[16:17], v[24:25] op_sel_hi:[1,0]
	ds_write2_b32 v19, v22, v23 offset1:1
	ds_write2_b32 v20, v24, v25 offset1:1
	s_cbranch_execnz .LBB0_1056

.LBB0_1056:
	s_waitcnt vmcnt(0)
	v_pk_mul_f32 v[10:11], v[10:11], v[18:19] op_sel_hi:[1,0]
	v_add_u32_e32 v14, 0x2490, v85
	ds_write2_b32 v14, v10, v11 offset1:1
	v_pk_mul_f32 v[10:11], v[12:13], v[18:19] op_sel_hi:[1,0]
	v_add_u32_e32 v12, 0x2498, v85
	ds_write2_b32 v12, v10, v11 offset1:1
	s_and_b64 vcc, exec, s[36:37]
	v_add_u32_e32 v11, 0x28a0, v85
	v_add_u32_e32 v12, 0x28a8, v85
	s_cbranch_vccnz .LBB0_1065
	s_ashr_i32 s7, s6, 31
	v_lshl_add_u64 v[14:15], s[6:7], 0, v[66:67]
	v_lshl_add_u64 v[14:15], v[14:15], 2, s[72:73]
	v_mov_b32_e32 v16, v136
	v_mov_b32_e32 v10, v137
	s_waitcnt vmcnt(1)
	v_pk_mul_f32 v[14:15], v[6:7], v[16:17] op_sel_hi:[1,0]
	v_pk_mul_f32 v[16:17], v[8:9], v[16:17] op_sel_hi:[1,0]
	ds_write2_b32 v11, v14, v15 offset1:1
	ds_write2_b32 v12, v16, v17 offset1:1
	s_cbranch_execnz .LBB0_1034
	s_branch .LBB0_1033

.LBB0_1115:
	s_or_b64 exec, exec, s[10:11]
	v_readlane_b32 s10, v253, 22
	v_readlane_b32 s11, v253, 23
	s_andn2_b64 vcc, exec, s[10:11]
	s_nop 0
	v_cndmask_b32_e64 v0, 0, 1, s[10:11]
	v_cmp_ne_u32_e64 s[34:35], 1, v0
	s_cbranch_vccnz .LBB0_1138
	v_ashrrev_i32_e32 v83, 31, v82
	s_ashr_i32 s9, s8, 31
	v_lshl_add_u64 v[82:83], v[82:83], 2, s[80:81]
	v_lshl_add_u64 v[84:85], s[8:9], 0, v[66:67]
	global_load_dword v122, v[82:83], off
	global_load_dword v123, v[82:83], off offset:16
	global_load_dword v124, v[82:83], off offset:32
	global_load_dword v125, v[82:83], off offset:48
	global_load_dword v126, v[82:83], off offset:64
	global_load_dword v127, v[82:83], off offset:80
	global_load_dword v128, v[82:83], off offset:96
	global_load_dword v129, v[82:83], off offset:112
	global_load_dword v130, v[82:83], off offset:128
	global_load_dword v131, v[82:83], off offset:144
	global_load_dword v132, v[82:83], off offset:160
	global_load_dword v133, v[82:83], off offset:176
	global_load_dword v134, v[82:83], off offset:192
	global_load_dword v135, v[82:83], off offset:208
	global_load_dword v136, v[82:83], off offset:224
	global_load_dword v137, v[82:83], off offset:240
	v_lshl_add_u64 v[84:85], v[84:85], 2, s[80:81]
	s_waitcnt vmcnt(0)
	v_mov_b32_e32 v82, v122
	v_mov_b32_e32 v0, v123
	v_pk_mul_f32 v[84:85], v[54:55], v[82:83] op_sel_hi:[1,0]
	v_pk_mul_f32 v[82:83], v[56:57], v[82:83] op_sel_hi:[1,0]
	ds_write2_b32 v69, v84, v85 offset1:1
	ds_write2_b32 v69, v82, v83 offset0:2 offset1:3
	s_cbranch_execnz .LBB0_1118

.LBB0_1118:
	s_waitcnt vmcnt(0)
	v_pk_mul_f32 v[30:31], v[30:31], v[0:1] op_sel_hi:[1,0]
	ds_write2_b32 v95, v30, v31 offset1:1
	v_pk_mul_f32 v[30:31], v[32:33], v[0:1] op_sel_hi:[1,0]
	s_and_b64 vcc, exec, s[34:35]
	ds_write2_b32 v95, v30, v31 offset0:2 offset1:3
	s_cbranch_vccnz .LBB0_1139
	s_ashr_i32 s9, s8, 31
	v_lshl_add_u64 v[30:31], s[8:9], 0, v[66:67]
	v_lshl_add_u64 v[30:31], v[30:31], 2, s[80:81]
	v_mov_b32_e32 v32, v124
	v_mov_b32_e32 v0, v125
	s_waitcnt vmcnt(1)
	v_pk_mul_f32 v[30:31], v[62:63], v[32:33] op_sel_hi:[1,0]
	v_pk_mul_f32 v[32:33], v[64:65], v[32:33] op_sel_hi:[1,0]
	ds_write2_b32 v97, v30, v31 offset1:1
	ds_write2_b32 v97, v32, v33 offset0:2 offset1:3
	s_cbranch_execnz .LBB0_1121

.LBB0_1121:
	s_waitcnt vmcnt(0)
	v_pk_mul_f32 v[30:31], v[34:35], v[0:1] op_sel_hi:[1,0]
	ds_write2_b32 v96, v30, v31 offset1:1
	v_pk_mul_f32 v[30:31], v[36:37], v[0:1] op_sel_hi:[1,0]
	s_and_b64 vcc, exec, s[34:35]
	ds_write2_b32 v96, v30, v31 offset0:2 offset1:3
	s_cbranch_vccnz .LBB0_1140
	s_ashr_i32 s9, s8, 31
	v_lshl_add_u64 v[30:31], s[8:9], 0, v[66:67]
	v_lshl_add_u64 v[30:31], v[30:31], 2, s[80:81]
	v_mov_b32_e32 v32, v126
	v_mov_b32_e32 v0, v127
	s_waitcnt vmcnt(1)
	v_pk_mul_f32 v[30:31], v[58:59], v[32:33] op_sel_hi:[1,0]
	v_pk_mul_f32 v[32:33], v[60:61], v[32:33] op_sel_hi:[1,0]
	ds_write2_b32 v98, v30, v31 offset1:1
	ds_write2_b32 v98, v32, v33 offset0:2 offset1:3
	s_cbranch_execnz .LBB0_1124

.LBB0_1124:
	s_waitcnt vmcnt(0)
	v_pk_mul_f32 v[26:27], v[26:27], v[0:1] op_sel_hi:[1,0]
	v_add_u32_e32 v30, 0x410, v98
	ds_write2_b32 v30, v26, v27 offset1:1
	v_pk_mul_f32 v[26:27], v[28:29], v[0:1] op_sel_hi:[1,0]
	v_add_u32_e32 v0, 0x418, v98
	ds_write2_b32 v0, v26, v27 offset1:1
	s_and_b64 vcc, exec, s[34:35]
	v_add_u32_e32 v26, 0x820, v98
	v_add_u32_e32 v27, 0x828, v98
	s_cbranch_vccnz .LBB0_1141
	s_ashr_i32 s9, s8, 31
	v_lshl_add_u64 v[28:29], s[8:9], 0, v[66:67]
	v_lshl_add_u64 v[28:29], v[28:29], 2, s[80:81]
	v_mov_b32_e32 v30, v128
	v_mov_b32_e32 v0, v129
	s_waitcnt vmcnt(1)
	v_pk_mul_f32 v[28:29], v[50:51], v[30:31] op_sel_hi:[1,0]
	v_pk_mul_f32 v[30:31], v[52:53], v[30:31] op_sel_hi:[1,0]
	ds_write2_b32 v26, v28, v29 offset1:1
	ds_write2_b32 v27, v30, v31 offset1:1
	s_cbranch_execnz .LBB0_1127

.LBB0_1127:
	s_waitcnt vmcnt(0)
	v_pk_mul_f32 v[22:23], v[22:23], v[0:1] op_sel_hi:[1,0]
	v_add_u32_e32 v26, 0xc30, v98
	ds_write2_b32 v26, v22, v23 offset1:1
	v_pk_mul_f32 v[22:23], v[24:25], v[0:1] op_sel_hi:[1,0]
	v_add_u32_e32 v0, 0xc38, v98
	ds_write2_b32 v0, v22, v23 offset1:1
	s_and_b64 vcc, exec, s[34:35]
	v_add_u32_e32 v22, 0x1040, v98
	v_add_u32_e32 v23, 0x1048, v98
	s_cbranch_vccnz .LBB0_1142
	s_ashr_i32 s9, s8, 31
	v_lshl_add_u64 v[24:25], s[8:9], 0, v[66:67]
	v_lshl_add_u64 v[24:25], v[24:25], 2, s[80:81]
	v_mov_b32_e32 v26, v130
	v_mov_b32_e32 v0, v131
	s_waitcnt vmcnt(1)
	v_pk_mul_f32 v[24:25], v[46:47], v[26:27] op_sel_hi:[1,0]
	v_pk_mul_f32 v[26:27], v[48:49], v[26:27] op_sel_hi:[1,0]
	ds_write2_b32 v22, v24, v25 offset1:1
	ds_write2_b32 v23, v26, v27 offset1:1
	s_cbranch_execnz .LBB0_1130

.LBB0_1130:
	s_waitcnt vmcnt(0)
	v_pk_mul_f32 v[14:15], v[14:15], v[0:1] op_sel_hi:[1,0]
	v_add_u32_e32 v22, 0x1450, v98
	ds_write2_b32 v22, v14, v15 offset1:1
	v_pk_mul_f32 v[14:15], v[16:17], v[0:1] op_sel_hi:[1,0]
	v_add_u32_e32 v0, 0x1458, v98
	ds_write2_b32 v0, v14, v15 offset1:1
	s_and_b64 vcc, exec, s[34:35]
	v_add_u32_e32 v14, 0x1860, v98
	v_add_u32_e32 v15, 0x1868, v98
	s_cbranch_vccnz .LBB0_1143
	s_ashr_i32 s9, s8, 31
	v_lshl_add_u64 v[16:17], s[8:9], 0, v[66:67]
	v_lshl_add_u64 v[16:17], v[16:17], 2, s[80:81]
	v_mov_b32_e32 v22, v132
	v_mov_b32_e32 v0, v133
	s_waitcnt vmcnt(1)
	v_pk_mul_f32 v[16:17], v[42:43], v[22:23] op_sel_hi:[1,0]
	v_pk_mul_f32 v[22:23], v[44:45], v[22:23] op_sel_hi:[1,0]
	ds_write2_b32 v14, v16, v17 offset1:1
	ds_write2_b32 v15, v22, v23 offset1:1
	s_cbranch_execnz .LBB0_1133

.LBB0_1133:
	s_waitcnt vmcnt(0)
	v_pk_mul_f32 v[10:11], v[10:11], v[0:1] op_sel_hi:[1,0]
	v_add_u32_e32 v14, 0x1c70, v98
	ds_write2_b32 v14, v10, v11 offset1:1
	v_pk_mul_f32 v[10:11], v[12:13], v[0:1] op_sel_hi:[1,0]
	v_add_u32_e32 v0, 0x1c78, v98
	ds_write2_b32 v0, v10, v11 offset1:1
	s_and_b64 vcc, exec, s[34:35]
	v_add_u32_e32 v10, 0x2080, v98
	v_add_u32_e32 v11, 0x2088, v98
	s_cbranch_vccnz .LBB0_1144
	s_ashr_i32 s9, s8, 31
	v_lshl_add_u64 v[12:13], s[8:9], 0, v[66:67]
	v_lshl_add_u64 v[12:13], v[12:13], 2, s[80:81]
	v_mov_b32_e32 v14, v134
	v_mov_b32_e32 v0, v135
	s_waitcnt vmcnt(1)
	v_pk_mul_f32 v[12:13], v[38:39], v[14:15] op_sel_hi:[1,0]
	v_pk_mul_f32 v[14:15], v[40:41], v[14:15] op_sel_hi:[1,0]
	ds_write2_b32 v10, v12, v13 offset1:1
	ds_write2_b32 v11, v14, v15 offset1:1
	s_cbranch_execnz .LBB0_1136

.LBB0_1136:
	s_waitcnt vmcnt(0)
	v_pk_mul_f32 v[6:7], v[6:7], v[0:1] op_sel_hi:[1,0]
	v_add_u32_e32 v10, 0x2490, v98
	ds_write2_b32 v10, v6, v7 offset1:1
	v_pk_mul_f32 v[6:7], v[8:9], v[0:1] op_sel_hi:[1,0]
	v_add_u32_e32 v0, 0x2498, v98
	ds_write2_b32 v0, v6, v7 offset1:1
	s_and_b64 vcc, exec, s[34:35]
	v_add_u32_e32 v6, 0x28a0, v98
	v_add_u32_e32 v7, 0x28a8, v98
	s_cbranch_vccnz .LBB0_1145
	s_ashr_i32 s9, s8, 31
	v_lshl_add_u64 v[8:9], s[8:9], 0, v[66:67]
	v_lshl_add_u64 v[8:9], v[8:9], 2, s[80:81]
	v_mov_b32_e32 v10, v136
	v_mov_b32_e32 v0, v137
	s_waitcnt vmcnt(1)
	v_pk_mul_f32 v[8:9], v[18:19], v[10:11] op_sel_hi:[1,0]
	v_pk_mul_f32 v[10:11], v[20:21], v[10:11] op_sel_hi:[1,0]
	ds_write2_b32 v6, v8, v9 offset1:1
	ds_write2_b32 v7, v10, v11 offset1:1
	s_cbranch_execnz .LBB0_1070
	s_branch .LBB0_1069
